# v45: v37 + GEMM K-loop head aligned to 64 bytes (code placement)
# speedup vs baseline: 1.0010x; 1.0010x over previous
; #define PG8_STAGE(bufoff, gbase, voff) do { _Pragma("unroll") for (int _i = 0; _i < 2; ++_i) \
;         __builtin_amdgcn_global_load_lds((const unsigned*)((const char*)(gbase) + (voff)[_i]), (LAS unsigned*)(lds + (bufoff) + ldsw + _i * 8192), 16, 0, 0); } while (0)
; #define PG8_LDA(dst, b, h) do { _Pragma("unroll") for (int m = 0; m < 4; ++m) _Pragma("unroll") for (int k = 0; k < 2; ++k) dst[m][k] = *(const LAS bf16x8*)(lds + PG8_SA(b, h) + aoff + m * 2048 + k * 1024); } while (0)
; #define PG8_LDB(dst, b, h) do { _Pragma("unroll") for (int n = 0; n < 2; ++n) _Pragma("unroll") for (int k = 0; k < 2; ++k) dst[n][k] = *(const LAS bf16x8*)(lds + PG8_SB(b, h) + boff + n * 2048 + k * 1024); } while (0)
; #define PG8_MMA(ai, bj, At, Bt) do { __builtin_amdgcn_s_setprio(3); _Pragma("unroll") for (int m = 0; m < 4; ++m) _Pragma("unroll") for (int n = 0; n < 2; ++n) _Pragma("unroll") for (int k = 0; k < 2; ++k) \
;         acc[ai][bj][m][n] = __builtin_amdgcn_mfma_f32_16x16x32_bf16(Bt[n][k], At[m][k], acc[ai][bj][m][n], 0, 0, 0); __builtin_amdgcn_s_setprio(0); } while (0)
; #define PG8_WAIT_V(n) asm volatile("s_waitcnt vmcnt(" #n ")" ::: "memory")
; #define PG8_WAIT_L(n) asm volatile("s_waitcnt lgkmcnt(" #n ")" ::: "memory")
; #define PG8_BAR __builtin_amdgcn_s_barrier()
; #define PG8_SCHED __builtin_amdgcn_sched_barrier(0)
; template <class Epi>
; __device__ __forceinline__ void gemm_phase(LAS unsigned char* lds, const Gemm g, const StaticOrder& S, const Epi& E, const int tid) {
;     ...
;             const bool last = (t == nt - 2);
;             const char* a1 = cA + (size_t)(t + 1) * kstep;
;             const char* a2 = last ? nA : cA + (size_t)(t + 2) * kstep; const char* b2 = last ? nB : cB + (size_t)(t + 2) * kstep;
;             const char* a3 = a2 + kstep; const char* b3 = b2 + kstep;
;             PG8_LDB(B0, 0, 0); PG8_LDB(B1, 0, 1); PG8_SCHED; PG8_LDA(At, 0, 0); PG8_STAGE(PG8_SA(1, 1), a1 + hstepA, voffA);
;             PG8_WAIT_V(8); PG8_WAIT_L(0); PG8_BAR; PG8_MMA(0, 0, At, B0); PG8_MMA(0, 1, At, B1); PG8_BAR; PG8_SCHED;
;             PG8_LDA(At, 0, 1); PG8_STAGE(PG8_SB(0, 0), b2, voffB); PG8_STAGE(PG8_SB(0, 1), b2 + hstepB, voffB); PG8_STAGE(PG8_SA(0, 0), a2, voffA);
;             PG8_WAIT_V(8); PG8_WAIT_L(0); PG8_BAR; PG8_MMA(1, 0, At, B0); PG8_MMA(1, 1, At, B1); PG8_BAR; PG8_SCHED;
.LBB0_264:
	s_add_u32 s30, s6, 0x100
	s_addc_u32 s31, s7, 0
	s_add_u32 s4, s20, 0x80
	s_addc_u32 s5, s21, 0
	s_mov_b32 s6, 0
	s_add_i32 s20, s6, 2
	s_add_u32 s21, s4, 0x80
	s_addc_u32 s7, s5, 0
	s_add_i32 s55, 0, 0x10000
	s_cmp_eq_u32 s48, s6
	s_cselect_b32 s7, s79, s7
	s_cselect_b32 s6, s78, s21
	s_cselect_b32 vcc_hi, s81, s31
	s_cselect_b32 vcc_lo, s80, s30
	s_add_i32 s21, 0, 0x14000
	v_add_u32_e32 v152, s55, v169
	v_add_u32_e32 v156, s21, v169
	ds_read_b128 v[140:143], v152
	ds_read_b128 v[144:147], v152 offset:1024
	ds_read_b128 v[148:151], v152 offset:2048
	ds_read_b128 v[152:155], v152 offset:3072
	ds_read_b128 v[172:175], v156
	ds_read_b128 v[180:183], v156 offset:1024
	ds_read_b128 v[184:187], v156 offset:2048
	ds_read_b128 v[194:197], v156 offset:3072
	v_lshl_add_u64 v[156:157], s[4:5], 0, v[138:139]
	s_add_i32 m0, s94, 0xc000
	ds_read_b128 v[198:201], v171
	ds_read_b128 v[202:205], v171 offset:1024
	ds_read_b128 v[206:209], v171 offset:2048
	ds_read_b128 v[210:213], v171 offset:3072
	ds_read_b128 v[214:217], v171 offset:4096
	ds_read_b128 v[218:221], v171 offset:5120
	ds_read_b128 v[222:225], v171 offset:6144
	ds_read_b128 v[226:229], v171 offset:7168
	global_load_lds_dwordx4 v[156:157], off
	v_lshl_add_u64 v[156:157], s[4:5], 0, v[136:137]
	s_add_i32 m0, s94, 0xe000
	s_nop 0
	global_load_lds_dwordx4 v[156:157], off
	s_waitcnt vmcnt(8)
	s_waitcnt lgkmcnt(0)
	s_barrier
	s_setprio 3
	s_waitcnt lgkmcnt(0)
	v_mfma_f32_16x16x32_bf16 v[124:127], v[140:143], v[198:201], 0
	v_mfma_f32_16x16x32_bf16 v[124:127], v[144:147], v[202:205], v[124:127]
	v_mfma_f32_16x16x32_bf16 v[116:119], v[140:143], v[206:209], 0
	v_mfma_f32_16x16x32_bf16 v[116:119], v[144:147], v[210:213], v[116:119]
	v_mfma_f32_16x16x32_bf16 v[100:103], v[140:143], v[214:217], 0
	v_mfma_f32_16x16x32_bf16 v[100:103], v[144:147], v[218:221], v[100:103]
	v_mfma_f32_16x16x32_bf16 v[84:87], v[140:143], v[222:225], 0
	v_mfma_f32_16x16x32_bf16 v[84:87], v[144:147], v[226:229], v[84:87]
	v_mfma_f32_16x16x32_bf16 v[120:123], v[148:151], v[198:201], 0
	v_mfma_f32_16x16x32_bf16 v[120:123], v[152:155], v[202:205], v[120:123]
	v_mfma_f32_16x16x32_bf16 v[108:111], v[148:151], v[206:209], 0
	v_mfma_f32_16x16x32_bf16 v[108:111], v[152:155], v[210:213], v[108:111]
	v_mfma_f32_16x16x32_bf16 v[92:95], v[148:151], v[214:217], 0
	v_mfma_f32_16x16x32_bf16 v[92:95], v[152:155], v[218:221], v[92:95]
	v_mfma_f32_16x16x32_bf16 v[76:79], v[148:151], v[222:225], 0
	v_mfma_f32_16x16x32_bf16 v[76:79], v[152:155], v[226:229], v[76:79]
	s_setprio 0
	s_setprio 3
	v_mfma_f32_16x16x32_bf16 v[112:115], v[172:175], v[198:201], 0
	v_mfma_f32_16x16x32_bf16 v[112:115], v[180:183], v[202:205], v[112:115]
	v_mfma_f32_16x16x32_bf16 v[96:99], v[172:175], v[206:209], 0
	v_mfma_f32_16x16x32_bf16 v[96:99], v[180:183], v[210:213], v[96:99]
	v_mfma_f32_16x16x32_bf16 v[80:83], v[172:175], v[214:217], 0
	v_mfma_f32_16x16x32_bf16 v[80:83], v[180:183], v[218:221], v[80:83]
	v_mfma_f32_16x16x32_bf16 v[68:71], v[172:175], v[222:225], 0
	v_mfma_f32_16x16x32_bf16 v[68:71], v[180:183], v[226:229], v[68:71]
	v_mfma_f32_16x16x32_bf16 v[104:107], v[184:187], v[198:201], 0
	v_mfma_f32_16x16x32_bf16 v[104:107], v[194:197], v[202:205], v[104:107]
	v_mfma_f32_16x16x32_bf16 v[88:91], v[184:187], v[206:209], 0
	v_mfma_f32_16x16x32_bf16 v[88:91], v[194:197], v[210:213], v[88:91]
	v_mfma_f32_16x16x32_bf16 v[72:75], v[184:187], v[214:217], 0
	v_mfma_f32_16x16x32_bf16 v[72:75], v[194:197], v[218:221], v[72:75]
	v_mfma_f32_16x16x32_bf16 v[64:67], v[184:187], v[222:225], 0
	v_mfma_f32_16x16x32_bf16 v[64:67], v[194:197], v[226:229], v[64:67]
	s_setprio 0
	s_barrier
	s_add_i32 s55, s55, s93
	v_lshl_add_u64 v[156:157], vcc, 0, v[130:131]
	s_mov_b32 m0, s55
	ds_read_b128 v[198:201], v171 offset:16384
	ds_read_b128 v[202:205], v171 offset:17408
	ds_read_b128 v[206:209], v171 offset:18432
	ds_read_b128 v[210:213], v171 offset:19456
	ds_read_b128 v[214:217], v171 offset:20480
	ds_read_b128 v[218:221], v171 offset:21504
	ds_read_b128 v[222:225], v171 offset:22528
	ds_read_b128 v[226:229], v171 offset:23552
	global_load_lds_dwordx4 v[156:157], off
	s_add_i32 m0, s55, 0x2000
	v_lshl_add_u64 v[190:191], vcc, 0, v[134:135]
	s_add_u32 vcc_lo, vcc_lo, s91
	s_addc_u32 vcc_hi, vcc_hi, 0
	s_add_i32 s21, s21, s93
	global_load_lds_dwordx4 v[190:191], off
	v_lshl_add_u64 v[240:241], vcc, 0, v[130:131]
	s_mov_b32 m0, s21
	v_lshl_add_u64 v[242:243], vcc, 0, v[134:135]
	global_load_lds_dwordx4 v[240:241], off
	s_add_i32 m0, s21, 0x2000
	v_lshl_add_u64 v[244:245], s[6:7], 0, v[128:129]
	global_load_lds_dwordx4 v[242:243], off
	s_mov_b32 m0, s94
	v_lshl_add_u64 v[246:247], s[6:7], 0, v[132:133]
	global_load_lds_dwordx4 v[244:245], off
	s_mov_b32 m0, s95
	s_nop 0
	global_load_lds_dwordx4 v[246:247], off
	s_waitcnt vmcnt(8)
	s_waitcnt lgkmcnt(0)
	s_barrier
; #define PG8_STAGE(bufoff, gbase, voff) do { _Pragma("unroll") for (int _i = 0; _i < 2; ++_i) \
;         __builtin_amdgcn_global_load_lds((const unsigned*)((const char*)(gbase) + (voff)[_i]), (LAS unsigned*)(lds + (bufoff) + ldsw + _i * 8192), 16, 0, 0); } while (0)
; #define PG8_LDA(dst, b, h) do { _Pragma("unroll") for (int m = 0; m < 4; ++m) _Pragma("unroll") for (int k = 0; k < 2; ++k) dst[m][k] = *(const LAS bf16x8*)(lds + PG8_SA(b, h) + aoff + m * 2048 + k * 1024); } while (0)
; #define PG8_LDB(dst, b, h) do { _Pragma("unroll") for (int n = 0; n < 2; ++n) _Pragma("unroll") for (int k = 0; k < 2; ++k) dst[n][k] = *(const LAS bf16x8*)(lds + PG8_SB(b, h) + boff + n * 2048 + k * 1024); } while (0)
; #define PG8_MMA(ai, bj, At, Bt) do { __builtin_amdgcn_s_setprio(3); _Pragma("unroll") for (int m = 0; m < 4; ++m) _Pragma("unroll") for (int n = 0; n < 2; ++n) _Pragma("unroll") for (int k = 0; k < 2; ++k) \
;         acc[ai][bj][m][n] = __builtin_amdgcn_mfma_f32_16x16x32_bf16(Bt[n][k], At[m][k], acc[ai][bj][m][n], 0, 0, 0); __builtin_amdgcn_s_setprio(0); } while (0)
; #define PG8_WAIT_V(n) asm volatile("s_waitcnt vmcnt(" #n ")" ::: "memory")
; #define PG8_WAIT_L(n) asm volatile("s_waitcnt lgkmcnt(" #n ")" ::: "memory")
; #define PG8_BAR __builtin_amdgcn_s_barrier()
; #define PG8_SCHED __builtin_amdgcn_sched_barrier(0)
; template <class Epi>
; __device__ __forceinline__ void gemm_phase(LAS unsigned char* lds, const Gemm g, const StaticOrder& S, const Epi& E, const int tid) {
;     ...
;             PG8_WAIT_V(8); PG8_WAIT_L(0); PG8_BAR; PG8_MMA(1, 0, At, B0); PG8_MMA(1, 1, At, B1); PG8_BAR; PG8_SCHED;
;             PG8_LDB(B0, 1, 0); PG8_LDB(B1, 1, 1); PG8_SCHED; PG8_LDA(At, 1, 0); PG8_STAGE(PG8_SA(0, 1), a2 + hstepA, voffA);
;             PG8_WAIT_V(8); PG8_WAIT_L(0); PG8_BAR; PG8_MMA(0, 0, At, B0); PG8_MMA(0, 1, At, B1); PG8_BAR; PG8_SCHED;
	s_setprio 3
	s_waitcnt lgkmcnt(0)
	v_mfma_f32_16x16x32_bf16 v[60:63], v[140:143], v[198:201], 0
	v_mfma_f32_16x16x32_bf16 v[60:63], v[144:147], v[202:205], v[60:63]
	v_mfma_f32_16x16x32_bf16 v[48:51], v[140:143], v[206:209], 0
	v_mfma_f32_16x16x32_bf16 v[48:51], v[144:147], v[210:213], v[48:51]
	v_mfma_f32_16x16x32_bf16 v[32:35], v[140:143], v[214:217], 0
	v_mfma_f32_16x16x32_bf16 v[32:35], v[144:147], v[218:221], v[32:35]
	v_mfma_f32_16x16x32_bf16 v[16:19], v[140:143], v[222:225], 0
	v_mfma_f32_16x16x32_bf16 v[16:19], v[144:147], v[226:229], v[16:19]
	v_mfma_f32_16x16x32_bf16 v[56:59], v[148:151], v[198:201], 0
	v_mfma_f32_16x16x32_bf16 v[56:59], v[152:155], v[202:205], v[56:59]
	v_mfma_f32_16x16x32_bf16 v[40:43], v[148:151], v[206:209], 0
	v_mfma_f32_16x16x32_bf16 v[40:43], v[152:155], v[210:213], v[40:43]
	v_mfma_f32_16x16x32_bf16 v[24:27], v[148:151], v[214:217], 0
	v_mfma_f32_16x16x32_bf16 v[24:27], v[152:155], v[218:221], v[24:27]
	v_mfma_f32_16x16x32_bf16 v[8:11], v[148:151], v[222:225], 0
	v_mfma_f32_16x16x32_bf16 v[8:11], v[152:155], v[226:229], v[8:11]
	s_setprio 0
	s_setprio 3
	v_mfma_f32_16x16x32_bf16 v[52:55], v[172:175], v[198:201], 0
	v_mfma_f32_16x16x32_bf16 v[52:55], v[180:183], v[202:205], v[52:55]
	v_mfma_f32_16x16x32_bf16 v[36:39], v[172:175], v[206:209], 0
	v_mfma_f32_16x16x32_bf16 v[36:39], v[180:183], v[210:213], v[36:39]
	v_mfma_f32_16x16x32_bf16 v[20:23], v[172:175], v[214:217], 0
	v_mfma_f32_16x16x32_bf16 v[20:23], v[180:183], v[218:221], v[20:23]
	v_mfma_f32_16x16x32_bf16 v[4:7], v[172:175], v[222:225], 0
	v_mfma_f32_16x16x32_bf16 v[4:7], v[180:183], v[226:229], v[4:7]
	v_mfma_f32_16x16x32_bf16 v[44:47], v[184:187], v[198:201], 0
	v_mfma_f32_16x16x32_bf16 v[44:47], v[194:197], v[202:205], v[44:47]
	v_mfma_f32_16x16x32_bf16 v[28:31], v[184:187], v[206:209], 0
	v_mfma_f32_16x16x32_bf16 v[28:31], v[194:197], v[210:213], v[28:31]
	v_mfma_f32_16x16x32_bf16 v[12:15], v[184:187], v[214:217], 0
	v_mfma_f32_16x16x32_bf16 v[12:15], v[194:197], v[218:221], v[12:15]
	v_mfma_f32_16x16x32_bf16 v[0:3], v[184:187], v[222:225], 0
	v_mfma_f32_16x16x32_bf16 v[0:3], v[194:197], v[226:229], v[0:3]
	s_setprio 0
	s_barrier
	s_add_i32 s21, 0, 0x18000
	s_add_i32 s55, 0, 0x1c000
	v_add_u32_e32 v152, s21, v169
	v_add_u32_e32 v176, s55, v169
	ds_read_b128 v[140:143], v152
	ds_read_b128 v[144:147], v152 offset:1024
	ds_read_b128 v[148:151], v152 offset:2048
	ds_read_b128 v[152:155], v152 offset:3072
	ds_read_b128 v[172:175], v176
	ds_read_b128 v[180:183], v176 offset:1024
	ds_read_b128 v[184:187], v176 offset:2048
	ds_read_b128 v[194:197], v176 offset:3072
	s_add_u32 s6, s6, s26
	s_addc_u32 s7, s7, 0
	s_mov_b32 m0, s96
	v_lshl_add_u64 v[252:253], s[6:7], 0, v[128:129]
	ds_read_b128 v[198:201], v171 offset:32768
	ds_read_b128 v[202:205], v171 offset:33792
	ds_read_b128 v[206:209], v171 offset:34816
	ds_read_b128 v[210:213], v171 offset:35840
	ds_read_b128 v[214:217], v171 offset:36864
	ds_read_b128 v[218:221], v171 offset:37888
	ds_read_b128 v[222:225], v171 offset:38912
	ds_read_b128 v[226:229], v171 offset:39936
	global_load_lds_dwordx4 v[252:253], off
	v_lshl_add_u64 v[252:253], s[6:7], 0, v[132:133]
	s_mov_b32 m0, s97
	s_nop 0
	global_load_lds_dwordx4 v[252:253], off
	s_waitcnt vmcnt(8)
	s_waitcnt lgkmcnt(0)
	s_barrier
	s_setprio 3
	s_waitcnt lgkmcnt(0)
	v_mfma_f32_16x16x32_bf16 v[124:127], v[140:143], v[198:201], v[124:127]
	v_mfma_f32_16x16x32_bf16 v[124:127], v[144:147], v[202:205], v[124:127]
	v_mfma_f32_16x16x32_bf16 v[116:119], v[140:143], v[206:209], v[116:119]
	v_mfma_f32_16x16x32_bf16 v[116:119], v[144:147], v[210:213], v[116:119]
	v_mfma_f32_16x16x32_bf16 v[100:103], v[140:143], v[214:217], v[100:103]
	v_mfma_f32_16x16x32_bf16 v[100:103], v[144:147], v[218:221], v[100:103]
	v_mfma_f32_16x16x32_bf16 v[84:87], v[140:143], v[222:225], v[84:87]
	v_mfma_f32_16x16x32_bf16 v[84:87], v[144:147], v[226:229], v[84:87]
	v_mfma_f32_16x16x32_bf16 v[120:123], v[148:151], v[198:201], v[120:123]
	v_mfma_f32_16x16x32_bf16 v[120:123], v[152:155], v[202:205], v[120:123]
	v_mfma_f32_16x16x32_bf16 v[108:111], v[148:151], v[206:209], v[108:111]
	v_mfma_f32_16x16x32_bf16 v[108:111], v[152:155], v[210:213], v[108:111]
	v_mfma_f32_16x16x32_bf16 v[92:95], v[148:151], v[214:217], v[92:95]
	v_mfma_f32_16x16x32_bf16 v[92:95], v[152:155], v[218:221], v[92:95]
	v_mfma_f32_16x16x32_bf16 v[76:79], v[148:151], v[222:225], v[76:79]
	v_mfma_f32_16x16x32_bf16 v[76:79], v[152:155], v[226:229], v[76:79]
	s_setprio 0
	s_setprio 3
	v_mfma_f32_16x16x32_bf16 v[112:115], v[172:175], v[198:201], v[112:115]
	v_mfma_f32_16x16x32_bf16 v[112:115], v[180:183], v[202:205], v[112:115]
	v_mfma_f32_16x16x32_bf16 v[96:99], v[172:175], v[206:209], v[96:99]
	v_mfma_f32_16x16x32_bf16 v[96:99], v[180:183], v[210:213], v[96:99]
	v_mfma_f32_16x16x32_bf16 v[80:83], v[172:175], v[214:217], v[80:83]
	v_mfma_f32_16x16x32_bf16 v[80:83], v[180:183], v[218:221], v[80:83]
	v_mfma_f32_16x16x32_bf16 v[68:71], v[172:175], v[222:225], v[68:71]
	v_mfma_f32_16x16x32_bf16 v[68:71], v[180:183], v[226:229], v[68:71]
	v_mfma_f32_16x16x32_bf16 v[104:107], v[184:187], v[198:201], v[104:107]
	v_mfma_f32_16x16x32_bf16 v[104:107], v[194:197], v[202:205], v[104:107]
	v_mfma_f32_16x16x32_bf16 v[88:91], v[184:187], v[206:209], v[88:91]
	v_mfma_f32_16x16x32_bf16 v[88:91], v[194:197], v[210:213], v[88:91]
	v_mfma_f32_16x16x32_bf16 v[72:75], v[184:187], v[214:217], v[72:75]
	v_mfma_f32_16x16x32_bf16 v[72:75], v[194:197], v[218:221], v[72:75]
	v_mfma_f32_16x16x32_bf16 v[64:67], v[184:187], v[222:225], v[64:67]
	v_mfma_f32_16x16x32_bf16 v[64:67], v[194:197], v[226:229], v[64:67]
	s_setprio 0
	s_barrier
; #define PG8_STAGE(bufoff, gbase, voff) do { _Pragma("unroll") for (int _i = 0; _i < 2; ++_i) \
;         __builtin_amdgcn_global_load_lds((const unsigned*)((const char*)(gbase) + (voff)[_i]), (LAS unsigned*)(lds + (bufoff) + ldsw + _i * 8192), 16, 0, 0); } while (0)
; #define PG8_LDA(dst, b, h) do { _Pragma("unroll") for (int m = 0; m < 4; ++m) _Pragma("unroll") for (int k = 0; k < 2; ++k) dst[m][k] = *(const LAS bf16x8*)(lds + PG8_SA(b, h) + aoff + m * 2048 + k * 1024); } while (0)
; #define PG8_MMA(ai, bj, At, Bt) do { __builtin_amdgcn_s_setprio(3); _Pragma("unroll") for (int m = 0; m < 4; ++m) _Pragma("unroll") for (int n = 0; n < 2; ++n) _Pragma("unroll") for (int k = 0; k < 2; ++k) \
;         acc[ai][bj][m][n] = __builtin_amdgcn_mfma_f32_16x16x32_bf16(Bt[n][k], At[m][k], acc[ai][bj][m][n], 0, 0, 0); __builtin_amdgcn_s_setprio(0); } while (0)
; #define PG8_WAIT_V(n) asm volatile("s_waitcnt vmcnt(" #n ")" ::: "memory")
; #define PG8_WAIT_L(n) asm volatile("s_waitcnt lgkmcnt(" #n ")" ::: "memory")
; #define PG8_BAR __builtin_amdgcn_s_barrier()
; #define PG8_SCHED __builtin_amdgcn_sched_barrier(0)
; template <class Epi>
; __device__ __forceinline__ void gemm_phase(LAS unsigned char* lds, const Gemm g, const StaticOrder& S, const Epi& E, const int tid) {
;     ...
;             PG8_LDA(At, 1, 1); PG8_STAGE(PG8_SB(1, 0), b3, voffB); PG8_STAGE(PG8_SB(1, 1), b3 + hstepB, voffB); PG8_STAGE(PG8_SA(1, 0), a3, voffA);
;             PG8_WAIT_V(8); PG8_WAIT_L(0); PG8_BAR; PG8_MMA(1, 0, At, B0); PG8_MMA(1, 1, At, B1); PG8_BAR; PG8_SCHED;
	s_add_i32 s6, s21, s93
	v_lshl_add_u64 v[156:157], v[156:157], 0, s[22:23]
	s_mov_b32 m0, s6
	ds_read_b128 v[198:201], v171 offset:49152
	ds_read_b128 v[202:205], v171 offset:50176
	ds_read_b128 v[206:209], v171 offset:51200
	ds_read_b128 v[210:213], v171 offset:52224
	ds_read_b128 v[214:217], v171 offset:53248
	ds_read_b128 v[218:221], v171 offset:54272
	ds_read_b128 v[222:225], v171 offset:55296
	ds_read_b128 v[226:229], v171 offset:56320
	global_load_lds_dwordx4 v[156:157], off
	v_lshl_add_u64 v[156:157], v[190:191], 0, s[22:23]
	s_add_i32 m0, s6, 0x2000
	s_add_i32 s6, s55, s93
	global_load_lds_dwordx4 v[156:157], off
	v_lshl_add_u64 v[156:157], v[240:241], 0, s[22:23]
	s_mov_b32 m0, s6
	s_nop 0
	global_load_lds_dwordx4 v[156:157], off
	v_lshl_add_u64 v[156:157], v[242:243], 0, s[22:23]
	s_add_i32 m0, s6, 0x2000
	s_nop 0
	global_load_lds_dwordx4 v[156:157], off
	v_lshl_add_u64 v[156:157], v[244:245], 0, s[22:23]
	s_mov_b32 m0, s98
	s_nop 0
	global_load_lds_dwordx4 v[156:157], off
	v_lshl_add_u64 v[156:157], v[246:247], 0, s[22:23]
	s_mov_b32 m0, s99
	s_nop 0
	global_load_lds_dwordx4 v[156:157], off
	s_waitcnt vmcnt(8)
	s_waitcnt lgkmcnt(0)
	s_barrier
	s_setprio 3
	s_waitcnt lgkmcnt(0)
	v_mfma_f32_16x16x32_bf16 v[60:63], v[140:143], v[198:201], v[60:63]
	v_mfma_f32_16x16x32_bf16 v[60:63], v[144:147], v[202:205], v[60:63]
	v_mfma_f32_16x16x32_bf16 v[48:51], v[140:143], v[206:209], v[48:51]
	v_mfma_f32_16x16x32_bf16 v[48:51], v[144:147], v[210:213], v[48:51]
	v_mfma_f32_16x16x32_bf16 v[32:35], v[140:143], v[214:217], v[32:35]
	v_mfma_f32_16x16x32_bf16 v[32:35], v[144:147], v[218:221], v[32:35]
	v_mfma_f32_16x16x32_bf16 v[16:19], v[140:143], v[222:225], v[16:19]
	v_mfma_f32_16x16x32_bf16 v[16:19], v[144:147], v[226:229], v[16:19]
	v_mfma_f32_16x16x32_bf16 v[56:59], v[148:151], v[198:201], v[56:59]
	v_mfma_f32_16x16x32_bf16 v[56:59], v[152:155], v[202:205], v[56:59]
	v_mfma_f32_16x16x32_bf16 v[40:43], v[148:151], v[206:209], v[40:43]
	v_mfma_f32_16x16x32_bf16 v[40:43], v[152:155], v[210:213], v[40:43]
	v_mfma_f32_16x16x32_bf16 v[24:27], v[148:151], v[214:217], v[24:27]
	v_mfma_f32_16x16x32_bf16 v[24:27], v[152:155], v[218:221], v[24:27]
	v_mfma_f32_16x16x32_bf16 v[8:11], v[148:151], v[222:225], v[8:11]
	v_mfma_f32_16x16x32_bf16 v[8:11], v[152:155], v[226:229], v[8:11]
	s_setprio 0
	s_setprio 3
	v_mfma_f32_16x16x32_bf16 v[52:55], v[172:175], v[198:201], v[52:55]
	v_mfma_f32_16x16x32_bf16 v[52:55], v[180:183], v[202:205], v[52:55]
	v_mfma_f32_16x16x32_bf16 v[36:39], v[172:175], v[206:209], v[36:39]
	v_mfma_f32_16x16x32_bf16 v[36:39], v[180:183], v[210:213], v[36:39]
	v_mfma_f32_16x16x32_bf16 v[20:23], v[172:175], v[214:217], v[20:23]
	v_mfma_f32_16x16x32_bf16 v[20:23], v[180:183], v[218:221], v[20:23]
	v_mfma_f32_16x16x32_bf16 v[4:7], v[172:175], v[222:225], v[4:7]
	v_mfma_f32_16x16x32_bf16 v[4:7], v[180:183], v[226:229], v[4:7]
	v_mfma_f32_16x16x32_bf16 v[44:47], v[184:187], v[198:201], v[44:47]
	v_mfma_f32_16x16x32_bf16 v[44:47], v[194:197], v[202:205], v[44:47]
	v_mfma_f32_16x16x32_bf16 v[28:31], v[184:187], v[206:209], v[28:31]
	v_mfma_f32_16x16x32_bf16 v[28:31], v[194:197], v[210:213], v[28:31]
	v_mfma_f32_16x16x32_bf16 v[12:15], v[184:187], v[214:217], v[12:15]
	v_mfma_f32_16x16x32_bf16 v[12:15], v[194:197], v[218:221], v[12:15]
	v_mfma_f32_16x16x32_bf16 v[0:3], v[184:187], v[222:225], v[0:3]
	v_mfma_f32_16x16x32_bf16 v[0:3], v[194:197], v[226:229], v[0:3]
	s_setprio 0
	s_barrier
	s_add_u32 s30, s30, 0x100
	s_addc_u32 s31, s31, 0
	s_add_u32 s4, s4, 0x100
	s_addc_u32 s5, s5, 0
	s_cmp_ge_u32 s20, s89
	s_mov_b32 s6, s20
	s_cbranch_scc1 .Lpg_kloop_done
	.p2align 6
